# bit-identical stack on the best file: GEMM1 gate epilogue lower-bound quads loaded together + dead address arithmetic removed; combine phase: 16-lane sum by DPP, loop-invariant norm gain quads hoisted
# speedup vs baseline: 1.0078x; 1.0059x over previous
.LBB0_473:
	s_andn2_b64 vcc, exec, s[0:1]
	s_cbranch_vccnz .LBB0_531
	v_mov_b32_e32 v4, v228
	v_readlane_b32 s0, v252, 33
	v_readlane_b32 s1, v252, 34
	v_ashrrev_i32_e32 v5, 31, v4
	s_mov_b32 s24, s19
	v_lshl_add_u64 v[0:1], s[0:1], 0, v[4:5]
	s_mov_b64 s[0:1], 0x440000
	s_mov_b64 s[38:39], s[22:23]
	v_cmp_gt_u64_e32 vcc, s[0:1], v[0:1]
	s_and_saveexec_b64 s[0:1], vcc
	v_readlane_b32 s8, v253, 2
	v_readlane_b32 s10, v253, 4
	v_readlane_b32 s11, v253, 5
	v_readlane_b32 s9, v253, 3
	v_readlane_b32 s12, v253, 6
	v_readlane_b32 s13, v253, 7
	v_readlane_b32 s14, v253, 8
	v_readlane_b32 s15, v253, 9
	v_readlane_b32 s16, v253, 10
	v_readlane_b32 s17, v253, 11
	v_readlane_b32 s18, v253, 12
	v_readlane_b32 s19, v253, 13
	v_readlane_b32 s20, v253, 14
	v_readlane_b32 s21, v253, 15
	v_readlane_b32 s22, v253, 16
	v_readlane_b32 s23, v253, 17
	s_cbranch_execz .LBB0_477
	v_and_b32_e32 v3, 64, v229
	v_xor_b32_e32 v2, 1, v229
	v_add_u32_e32 v3, 64, v3
	v_cmp_lt_i32_e32 vcc, v2, v3
	v_readlane_b32 s2, v253, 36
	v_readlane_b32 s3, v253, 37
	v_cndmask_b32_e32 v2, v229, v2, vcc
	v_lshlrev_b32_e32 v6, 2, v2
	v_xor_b32_e32 v2, 2, v229
	v_cmp_lt_i32_e32 vcc, v2, v3
	s_load_dword s80, s[2:3], 0x0
	v_readlane_b32 s6, v252, 50
	v_cndmask_b32_e32 v2, v229, v2, vcc
	v_lshlrev_b32_e32 v7, 2, v2
	v_xor_b32_e32 v2, 4, v229
	v_cmp_lt_i32_e32 vcc, v2, v3
	v_readlane_b32 s7, v252, 51
	s_waitcnt lgkmcnt(0)
	s_lshl_b64 s[2:3], s[80:81], 9
	v_cndmask_b32_e32 v2, v229, v2, vcc
	v_lshlrev_b32_e32 v8, 2, v2
	v_xor_b32_e32 v2, 8, v229
	v_cmp_lt_i32_e32 vcc, v2, v3
	s_lshl_b64 s[8:9], s[80:81], 13
	s_lshl_b64 s[12:13], s[80:81], 12
	v_cndmask_b32_e32 v2, v229, v2, vcc
	v_lshlrev_b32_e32 v9, 2, v2
	v_lshl_add_u64 v[2:3], v[4:5], 4, s[6:7]
	v_readlane_b32 s6, v252, 54
	v_readlane_b32 s7, v252, 55
	s_mov_b64 s[14:15], 0
	s_nop 0
	v_lshl_add_u64 v[4:5], v[4:5], 3, s[6:7]
	v_and_b32_e32 v42, 0x7f8, v4
	v_lshlrev_b32_e32 v42, 2, v42
	s_nop 0
	global_load_dwordx4 v[46:49], v42, s[10:11]
	global_load_dwordx4 v[42:45], v42, s[10:11] offset:16
.LBB0_476:
	v_add_co_u32_e32 v30, vcc, 0xfbc00000, v2
	s_nop 0
	v_addc_co_u32_e32 v31, vcc, -1, v3, vcc
	global_load_dwordx4 v[10:13], v[30:31], off nt
	global_load_dwordx4 v[14:17], v[2:3], off nt
	v_add_co_u32_e32 v18, vcc, 0xf7800000, v2
	s_mov_b32 s6, 0x800000
	s_nop 0
	v_addc_co_u32_e32 v19, vcc, -1, v3, vcc
	global_load_dwordx4 v[18:21], v[18:19], off nt
	v_lshl_add_u64 v[0:1], v[0:1], 0, s[2:3]
	v_lshl_add_u64 v[2:3], v[2:3], 0, s[8:9]
	v_lshl_add_u64 v[4:5], v[4:5], 0, s[12:13]
	s_waitcnt vmcnt(2)
	v_lshlrev_b32_e32 v22, 16, v13
	v_and_b32_e32 v23, 0xffff0000, v13
	s_waitcnt vmcnt(1)
	v_lshlrev_b32_e32 v24, 16, v17
	v_and_b32_e32 v25, 0xffff0000, v17
	v_pk_add_f32 v[32:33], v[22:23], v[24:25]
	v_lshlrev_b32_e32 v22, 16, v12
	v_and_b32_e32 v23, 0xffff0000, v12
	v_lshlrev_b32_e32 v12, 16, v16
	v_and_b32_e32 v13, 0xffff0000, v16
	v_pk_add_f32 v[12:13], v[22:23], v[12:13]
	v_mov_b32_e32 v22, v33
	v_mov_b32_e32 v23, v13
	v_mov_b32_e32 v16, v32
	v_mov_b32_e32 v17, v12
	v_pk_mul_f32 v[22:23], v[22:23], v[22:23]
	v_lshlrev_b32_e32 v36, 16, v11
	v_pk_fma_f32 v[16:17], v[16:17], v[16:17], v[22:23]
	s_nop 0
	v_and_b32_e32 v37, 0xffff0000, v11
	v_lshlrev_b32_e32 v38, 16, v15
	v_and_b32_e32 v39, 0xffff0000, v15
	v_lshlrev_b32_e32 v40, 16, v10
	v_and_b32_e32 v41, 0xffff0000, v10
	v_lshlrev_b32_e32 v10, 16, v14
	v_and_b32_e32 v11, 0xffff0000, v14
	v_pk_add_f32 v[36:37], v[36:37], v[38:39]
	v_pk_add_f32 v[10:11], v[40:41], v[10:11]
	v_mov_b32_e32 v41, v37
	v_mov_b32_e32 v40, v11
	v_mov_b32_e32 v14, v10
	v_mov_b32_e32 v15, v36
	v_pk_mul_f32 v[40:41], v[40:41], v[40:41]
	s_waitcnt vmcnt(0)
	v_lshlrev_b32_e32 v34, 16, v20
	v_pk_fma_f32 v[14:15], v[14:15], v[14:15], v[40:41]
	v_and_b32_e32 v35, 0xffff0000, v20
	v_add_f32_e32 v14, v14, v15
	v_add_f32_e32 v14, v17, v14
	v_add_f32_e32 v14, v16, v14
	v_lshlrev_b32_e32 v38, 16, v19
	v_and_b32_e32 v39, 0xffff0000, v19
	v_add_f32_dpp v14, v14, v14 quad_perm:[1,0,3,2] row_mask:0xf bank_mask:0xf
	v_lshlrev_b32_e32 v40, 16, v18
	v_and_b32_e32 v41, 0xffff0000, v18
	v_add_f32_dpp v14, v14, v14 quad_perm:[2,3,0,1] row_mask:0xf bank_mask:0xf
	v_lshlrev_b32_e32 v18, 16, v21
	v_and_b32_e32 v19, 0xffff0000, v21
	v_add_f32_dpp v14, v14, v14 row_half_mirror row_mask:0xf bank_mask:0xf
	s_nop 1
	v_add_f32_dpp v14, v14, v14 row_mirror row_mask:0xf bank_mask:0xf
	v_fmamk_f32 v14, v14, 0x3c000000, v205
	v_cmp_gt_f32_e32 vcc, s6, v14
	v_mul_f32_e32 v15, 0x4b800000, v14
	s_mov_b64 s[6:7], 0x43ffff
	v_cndmask_b32_e32 v14, v14, v15, vcc
	v_rsq_f32_e32 v14, v14
	s_nop 0
	v_mul_f32_e32 v15, 0x45800000, v14
	v_cndmask_b32_e32 v14, v14, v15, vcc
	v_pk_mul_f32 v[10:11], v[10:11], v[14:15] op_sel_hi:[1,0]
	v_pk_mul_f32 v[16:17], v[36:37], v[14:15] op_sel_hi:[1,0]
	v_pk_mul_f32 v[12:13], v[12:13], v[14:15] op_sel_hi:[1,0]
	v_pk_mul_f32 v[14:15], v[32:33], v[14:15] op_sel_hi:[1,0]
	v_cmp_lt_u64_e32 vcc, s[6:7], v[0:1]
	s_or_b64 s[14:15], vcc, s[14:15]
	v_pk_mul_f32 v[12:13], v[42:43], v[12:13]
	v_pk_mul_f32 v[10:11], v[46:47], v[10:11]
	v_pk_mul_f32 v[16:17], v[48:49], v[16:17]
	v_pk_mul_f32 v[14:15], v[44:45], v[14:15]
	v_pk_mul_f32 v[10:11], v[10:11], v[40:41]
	v_pk_mul_f32 v[16:17], v[16:17], v[38:39]
	v_pk_mul_f32 v[12:13], v[12:13], v[34:35]
	v_pk_mul_f32 v[14:15], v[14:15], v[18:19]
	v_cvt_pk_bf16_f32 v10, v10, v11
	v_cvt_pk_bf16_f32 v11, v16, v17
	v_cvt_pk_bf16_f32 v12, v12, v13
	v_cvt_pk_bf16_f32 v13, v14, v15
	global_store_dwordx4 v[30:31], v[10:13], off
	s_andn2_b64 exec, exec, s[14:15]
	s_cbranch_execnz .LBB0_476
